# placement check taken off the start of P1: census loads issued right after the first barrier, evaluated after the LDS staging loads
# speedup vs baseline: 1.0040x; 1.0040x over previous
.LBB0_115:
	v_cmp_eq_u32_e32 vcc, 0, v0
	s_and_saveexec_b64 s[2:3], vcc
	s_cbranch_execz .Llb_chk_done
	v_readlane_b32 s4, v254, 12
	v_readlane_b32 s5, v254, 13
	v_mov_b32_e32 v68, 0
	v_mov_b32_e32 v70, s88
	ds_write_b32 v70, v68 offset:8
	v_mov_b32_e32 v69, 0x2404
	v_mov_b32_e32 v71, 0x400
	s_nop 4
	global_load_dword v36, v69, s[4:5] sc1
	global_load_dword v37, v69, s[4:5] offset:256 sc1
	global_load_dword v38, v69, s[4:5] offset:512 sc1
	global_load_dword v39, v69, s[4:5] offset:768 sc1
	global_load_dword v40, v69, s[4:5] offset:1024 sc1
	global_load_dword v41, v69, s[4:5] offset:1280 sc1
	global_load_dword v42, v69, s[4:5] offset:1536 sc1
	global_load_dword v43, v69, s[4:5] offset:1792 sc1
	global_load_dword v44, v69, s[4:5] offset:2048 sc1
	global_load_dword v45, v69, s[4:5] offset:2304 sc1
	global_load_dword v46, v69, s[4:5] offset:2560 sc1
	global_load_dword v47, v69, s[4:5] offset:2816 sc1
	global_load_dword v48, v69, s[4:5] offset:3072 sc1
	global_load_dword v49, v69, s[4:5] offset:3328 sc1
	global_load_dword v50, v69, s[4:5] offset:3584 sc1
	global_load_dword v51, v69, s[4:5] offset:3840 sc1
	global_load_dword v52, v71, s[4:5] sc1
	global_load_dword v53, v71, s[4:5] offset:256 sc1
	global_load_dword v54, v71, s[4:5] offset:512 sc1
	global_load_dword v55, v71, s[4:5] offset:768 sc1
	global_load_dword v56, v71, s[4:5] offset:1024 sc1
	global_load_dword v57, v71, s[4:5] offset:1280 sc1
	global_load_dword v58, v71, s[4:5] offset:1536 sc1
	global_load_dword v59, v71, s[4:5] offset:1792 sc1
	global_load_dword v60, v71, s[4:5] offset:2048 sc1
	global_load_dword v61, v71, s[4:5] offset:2304 sc1
	global_load_dword v62, v71, s[4:5] offset:2560 sc1
	global_load_dword v63, v71, s[4:5] offset:2816 sc1
	global_load_dword v64, v71, s[4:5] offset:3072 sc1
	global_load_dword v65, v71, s[4:5] offset:3328 sc1
	global_load_dword v66, v71, s[4:5] offset:3584 sc1
	global_load_dword v67, v71, s[4:5] offset:3840 sc1
	s_waitcnt lgkmcnt(0)

.LBB0_118:
	s_or_b64 exec, exec, s[0:1]
	v_cmp_eq_u32_e32 vcc, 0, v0
	s_and_saveexec_b64 s[0:1], vcc
	s_cbranch_execz .Llb_chk_done2
	s_waitcnt vmcnt(0)
	v_mov_b32_e32 v69, 0
	v_add_u32_e32 v68, -1, v36
	v_and_b32_e32 v68, v68, v36
	v_or_b32_e32 v69, v69, v68
	v_add_u32_e32 v68, -1, v37
	v_and_b32_e32 v68, v68, v37
	v_or_b32_e32 v69, v69, v68
	v_add_u32_e32 v68, -1, v38
	v_and_b32_e32 v68, v68, v38
	v_or_b32_e32 v69, v69, v68
	v_add_u32_e32 v68, -1, v39
	v_and_b32_e32 v68, v68, v39
	v_or_b32_e32 v69, v69, v68
	v_add_u32_e32 v68, -1, v40
	v_and_b32_e32 v68, v68, v40
	v_or_b32_e32 v69, v69, v68
	v_add_u32_e32 v68, -1, v41
	v_and_b32_e32 v68, v68, v41
	v_or_b32_e32 v69, v69, v68
	v_add_u32_e32 v68, -1, v42
	v_and_b32_e32 v68, v68, v42
	v_or_b32_e32 v69, v69, v68
	v_add_u32_e32 v68, -1, v43
	v_and_b32_e32 v68, v68, v43
	v_or_b32_e32 v69, v69, v68
	v_add_u32_e32 v68, -1, v44
	v_and_b32_e32 v68, v68, v44
	v_or_b32_e32 v69, v69, v68
	v_add_u32_e32 v68, -1, v45
	v_and_b32_e32 v68, v68, v45
	v_or_b32_e32 v69, v69, v68
	v_add_u32_e32 v68, -1, v46
	v_and_b32_e32 v68, v68, v46
	v_or_b32_e32 v69, v69, v68
	v_add_u32_e32 v68, -1, v47
	v_and_b32_e32 v68, v68, v47
	v_or_b32_e32 v69, v69, v68
	v_add_u32_e32 v68, -1, v48
	v_and_b32_e32 v68, v68, v48
	v_or_b32_e32 v69, v69, v68
	v_add_u32_e32 v68, -1, v49
	v_and_b32_e32 v68, v68, v49
	v_or_b32_e32 v69, v69, v68
	v_add_u32_e32 v68, -1, v50
	v_and_b32_e32 v68, v68, v50
	v_or_b32_e32 v69, v69, v68
	v_add_u32_e32 v68, -1, v51
	v_and_b32_e32 v68, v68, v51
	v_or_b32_e32 v69, v69, v68
	v_subrev_u32_e32 v68, 32, v52
	v_mul_lo_u32 v68, v68, v52
	v_or_b32_e32 v69, v69, v68
	v_subrev_u32_e32 v68, 32, v53
	v_mul_lo_u32 v68, v68, v53
	v_or_b32_e32 v69, v69, v68
	v_subrev_u32_e32 v68, 32, v54
	v_mul_lo_u32 v68, v68, v54
	v_or_b32_e32 v69, v69, v68
	v_subrev_u32_e32 v68, 32, v55
	v_mul_lo_u32 v68, v68, v55
	v_or_b32_e32 v69, v69, v68
	v_subrev_u32_e32 v68, 32, v56
	v_mul_lo_u32 v68, v68, v56
	v_or_b32_e32 v69, v69, v68
	v_subrev_u32_e32 v68, 32, v57
	v_mul_lo_u32 v68, v68, v57
	v_or_b32_e32 v69, v69, v68
	v_subrev_u32_e32 v68, 32, v58
	v_mul_lo_u32 v68, v68, v58
	v_or_b32_e32 v69, v69, v68
	v_subrev_u32_e32 v68, 32, v59
	v_mul_lo_u32 v68, v68, v59
	v_or_b32_e32 v69, v69, v68
	v_subrev_u32_e32 v68, 32, v60
	v_mul_lo_u32 v68, v68, v60
	v_or_b32_e32 v69, v69, v68
	v_subrev_u32_e32 v68, 32, v61
	v_mul_lo_u32 v68, v68, v61
	v_or_b32_e32 v69, v69, v68
	v_subrev_u32_e32 v68, 32, v62
	v_mul_lo_u32 v68, v68, v62
	v_or_b32_e32 v69, v69, v68
	v_subrev_u32_e32 v68, 32, v63
	v_mul_lo_u32 v68, v68, v63
	v_or_b32_e32 v69, v69, v68
	v_subrev_u32_e32 v68, 32, v64
	v_mul_lo_u32 v68, v68, v64
	v_or_b32_e32 v69, v69, v68
	v_subrev_u32_e32 v68, 32, v65
	v_mul_lo_u32 v68, v68, v65
	v_or_b32_e32 v69, v69, v68
	v_subrev_u32_e32 v68, 32, v66
	v_mul_lo_u32 v68, v68, v66
	v_or_b32_e32 v69, v69, v68
	v_subrev_u32_e32 v68, 32, v67
	v_mul_lo_u32 v68, v68, v67
	v_or_b32_e32 v69, v69, v68
	v_mov_b32_e32 v71, s25
	v_xor_b32_e32 v71, 0x100, v71
	v_or_b32_e32 v69, v69, v71
	v_mov_b32_e32 v70, s88
	v_cmp_eq_u32_e32 vcc, 0, v69
	s_nop 1
	v_cndmask_b32_e64 v69, 0, 1, vcc
	ds_write_b32 v70, v69 offset:8
